# v11: v7 + v_add_f32_dpp fusion + layer-0 ctx copy store-ack waits removed
# baseline (speedup 1.0000x reference)
; __device__ __forceinline__ unsigned pk_bf16(float lo, float hi) { unsigned r; asm volatile("v_cvt_pk_bf16_f32 %0, %1, %2" : "=v"(r) : "v"(lo), "v"(hi)); return r; }
; __device__ __forceinline__ void phase_norm(int wv, const Params& p, int l, int which, int nrows, int nparts, const float* rgate) {
;     ...
;                 for (int q = 0; q < 4; ++q) {
;                     if (cpy) { u32x2 w; w.x = pk_bf16(v[u][q][0], v[u][q][1]); w.y = pk_bf16(v[u][q][2], v[u][q][3]); *(u32x2*)((bf16_t*)(p.ws + OFF_XB) + (size_t)row * 1024 + cq[q]) = w; }
;                     ss[u] += v[u][q][0] * v[u][q][0] + v[u][q][1] * v[u][q][1] + v[u][q][2] * v[u][q][2] + v[u][q][3] * v[u][q][3]; } } }
.LBB0_108:
	s_or_b64 exec, exec, s[4:5]
	s_and_saveexec_b64 s[0:1], s[6:7]
	s_xor_b64 s[4:5], exec, s[0:1]
	s_andn2_saveexec_b64 s[4:5], s[4:5]
	s_cbranch_execz .LBB0_110
	v_lshl_add_u64 v[54:55], v[90:91], 0, v[2:3]
	v_cvt_pk_bf16_f32 v52, v44, v45
	v_cvt_pk_bf16_f32 v53, v46, v47
	global_store_dwordx2 v[54:55], v[52:53], off
.LBB0_110:
	s_or_b64 exec, exec, s[4:5]
	s_and_saveexec_b64 s[0:1], s[6:7]
	s_xor_b64 s[4:5], exec, s[0:1]
	s_andn2_saveexec_b64 s[4:5], s[4:5]
	s_cbranch_execz .LBB0_115
	v_lshl_add_u64 v[54:55], v[96:97], 0, v[2:3]
	v_cvt_pk_bf16_f32 v52, v40, v41
	v_cvt_pk_bf16_f32 v53, v42, v43
	global_store_dwordx2 v[54:55], v[52:53], off
	s_or_b64 exec, exec, s[4:5]
	s_and_saveexec_b64 s[0:1], s[6:7]
	s_xor_b64 s[4:5], exec, s[0:1]
	s_cbranch_execnz .LBB0_116

; __device__ __forceinline__ unsigned pk_bf16(float lo, float hi) { unsigned r; asm volatile("v_cvt_pk_bf16_f32 %0, %1, %2" : "=v"(r) : "v"(lo), "v"(hi)); return r; }
; __device__ __forceinline__ void phase_norm(int wv, const Params& p, int l, int which, int nrows, int nparts, const float* rgate) {
;     ...
;                     if (cpy) { u32x2 w; w.x = pk_bf16(v[u][q][0], v[u][q][1]); w.y = pk_bf16(v[u][q][2], v[u][q][3]); *(u32x2*)((bf16_t*)(p.ws + OFF_XB) + (size_t)row * 1024 + cq[q]) = w; }
.LBB0_113:
	v_lshl_add_u64 v[2:3], v[92:93], 0, v[2:3]
	v_cvt_pk_bf16_f32 v52, v36, v37
	v_cvt_pk_bf16_f32 v53, v38, v39
	global_store_dwordx2 v[2:3], v[52:53], off
	s_or_b64 exec, exec, s[4:5]
	v_mov_b32_e32 v99, 0
	s_and_saveexec_b64 s[6:7], s[12:13]
	s_cbranch_execnz .LBB0_118

; __device__ __forceinline__ unsigned pk_bf16(float lo, float hi) { unsigned r; asm volatile("v_cvt_pk_bf16_f32 %0, %1, %2" : "=v"(r) : "v"(lo), "v"(hi)); return r; }
; __device__ __forceinline__ void phase_norm(int wv, const Params& p, int l, int which, int nrows, int nparts, const float* rgate) {
;     ...
;                 for (int q = 0; q < 4; ++q) {
;                     if (cpy) { u32x2 w; w.x = pk_bf16(v[u][q][0], v[u][q][1]); w.y = pk_bf16(v[u][q][2], v[u][q][3]); *(u32x2*)((bf16_t*)(p.ws + OFF_XB) + (size_t)row * 1024 + cq[q]) = w; }
;                     ss[u] += v[u][q][0] * v[u][q][0] + v[u][q][1] * v[u][q][1] + v[u][q][2] * v[u][q][2] + v[u][q][3] * v[u][q][3]; } } }
.LBB0_124:
	s_or_b64 exec, exec, s[4:5]
	s_and_saveexec_b64 s[0:1], s[14:15]
	s_xor_b64 s[4:5], exec, s[0:1]
	s_andn2_saveexec_b64 s[4:5], s[4:5]
	s_cbranch_execz .LBB0_126
	v_lshl_add_u64 v[54:55], v[90:91], 0, v[2:3]
	v_cvt_pk_bf16_f32 v52, v28, v29
	v_cvt_pk_bf16_f32 v53, v30, v31
	global_store_dwordx2 v[54:55], v[52:53], off
.LBB0_126:
	s_or_b64 exec, exec, s[4:5]
	s_and_saveexec_b64 s[0:1], s[14:15]
	s_xor_b64 s[4:5], exec, s[0:1]
	s_andn2_saveexec_b64 s[4:5], s[4:5]
	s_cbranch_execz .LBB0_158
	v_lshl_add_u64 v[54:55], v[96:97], 0, v[2:3]
	v_cvt_pk_bf16_f32 v52, v24, v25
	v_cvt_pk_bf16_f32 v53, v26, v27
	global_store_dwordx2 v[54:55], v[52:53], off
	s_or_b64 exec, exec, s[4:5]
	s_and_saveexec_b64 s[0:1], s[14:15]
	s_xor_b64 s[4:5], exec, s[0:1]
	s_cbranch_execnz .LBB0_159

; __device__ __forceinline__ unsigned pk_bf16(float lo, float hi) { unsigned r; asm volatile("v_cvt_pk_bf16_f32 %0, %1, %2" : "=v"(r) : "v"(lo), "v"(hi)); return r; }
; __device__ __forceinline__ void phase_norm(int wv, const Params& p, int l, int which, int nrows, int nparts, const float* rgate) {
;     ...
;                     if (cpy) { u32x2 w; w.x = pk_bf16(v[u][q][0], v[u][q][1]); w.y = pk_bf16(v[u][q][2], v[u][q][3]); *(u32x2*)((bf16_t*)(p.ws + OFF_XB) + (size_t)row * 1024 + cq[q]) = w; }
.LBB0_129:
	v_lshl_add_u64 v[2:3], v[92:93], 0, v[2:3]
	v_cvt_pk_bf16_f32 v52, v20, v21
	v_cvt_pk_bf16_f32 v53, v22, v23
	global_store_dwordx2 v[2:3], v[52:53], off

; __device__ __forceinline__ unsigned pk_bf16(float lo, float hi) { unsigned r; asm volatile("v_cvt_pk_bf16_f32 %0, %1, %2" : "=v"(r) : "v"(lo), "v"(hi)); return r; }
; __device__ __forceinline__ void phase_norm(int wv, const Params& p, int l, int which, int nrows, int nparts, const float* rgate) {
;     ...
;                 for (int q = 0; q < 4; ++q) {
;                     if (cpy) { u32x2 w; w.x = pk_bf16(v[u][q][0], v[u][q][1]); w.y = pk_bf16(v[u][q][2], v[u][q][3]); *(u32x2*)((bf16_t*)(p.ws + OFF_XB) + (size_t)row * 1024 + cq[q]) = w; }
;                     ss[u] += v[u][q][0] * v[u][q][0] + v[u][q][1] * v[u][q][1] + v[u][q][2] * v[u][q][2] + v[u][q][3] * v[u][q][3]; } } }
.LBB0_137:
	s_or_b64 exec, exec, s[4:5]
	s_and_saveexec_b64 s[0:1], s[14:15]
	s_xor_b64 s[4:5], exec, s[0:1]
	s_andn2_saveexec_b64 s[4:5], s[4:5]
	s_cbranch_execz .LBB0_139
	v_lshl_add_u64 v[54:55], v[90:91], 0, v[2:3]
	v_cvt_pk_bf16_f32 v52, v12, v13
	v_cvt_pk_bf16_f32 v53, v14, v15
	global_store_dwordx2 v[54:55], v[52:53], off
.LBB0_139:
	s_or_b64 exec, exec, s[4:5]
	s_and_saveexec_b64 s[0:1], s[14:15]
	s_xor_b64 s[4:5], exec, s[0:1]
	s_andn2_saveexec_b64 s[4:5], s[4:5]
	s_cbranch_execz .LBB0_160
	v_lshl_add_u64 v[54:55], v[96:97], 0, v[2:3]
	v_cvt_pk_bf16_f32 v52, v8, v9
	v_cvt_pk_bf16_f32 v53, v10, v11
	global_store_dwordx2 v[54:55], v[52:53], off
	s_or_b64 exec, exec, s[4:5]
	s_and_saveexec_b64 s[0:1], s[14:15]
	s_xor_b64 s[4:5], exec, s[0:1]
	s_cbranch_execnz .LBB0_161

; __device__ __forceinline__ unsigned pk_bf16(float lo, float hi) { unsigned r; asm volatile("v_cvt_pk_bf16_f32 %0, %1, %2" : "=v"(r) : "v"(lo), "v"(hi)); return r; }
; __device__ __forceinline__ void phase_norm(int wv, const Params& p, int l, int which, int nrows, int nparts, const float* rgate) {
;     ...
;                 for (int q = 0; q < 4; ++q) {
;                     if (cpy) { u32x2 w; w.x = pk_bf16(v[u][q][0], v[u][q][1]); w.y = pk_bf16(v[u][q][2], v[u][q][3]); *(u32x2*)((bf16_t*)(p.ws + OFF_XB) + (size_t)row * 1024 + cq[q]) = w; }
;                     ss[u] += v[u][q][0] * v[u][q][0] + v[u][q][1] * v[u][q][1] + v[u][q][2] * v[u][q][2] + v[u][q][3] * v[u][q][3]; } } }
.LBB0_142:
	v_lshl_add_u64 v[2:3], v[92:93], 0, v[2:3]
	v_cvt_pk_bf16_f32 v52, v4, v5
	v_cvt_pk_bf16_f32 v53, v6, v7
	global_store_dwordx2 v[2:3], v[52:53], off

; #define LAS __attribute__((address_space(3)))
; __device__ __forceinline__ unsigned pk_bf16(float lo, float hi) { unsigned r; asm volatile("v_cvt_pk_bf16_f32 %0, %1, %2" : "=v"(r) : "v"(lo), "v"(hi)); return r; }
; __device__ __forceinline__ float bflo(unsigned w) { return __uint_as_float(w << 16); }
; __device__ __forceinline__ float bfhi(unsigned w) { return __uint_as_float(w & 0xffff0000u); }
; __device__ __forceinline__ float shx(float v, int m, int lane) { return __int_as_float(__builtin_amdgcn_ds_bpermute((lane ^ m) << 2, __float_as_int(v))); }
; __device__ __forceinline__ u32x4 norm_krow(u32x4 w, int lane) {
;     float v[8]; v[0] = bflo(w.x); v[1] = bfhi(w.x); v[2] = bflo(w.y); v[3] = bfhi(w.y); v[4] = bflo(w.z); v[5] = bfhi(w.z); v[6] = bflo(w.w); v[7] = bfhi(w.w);
;     float ss = 0.f;
; #pragma unroll
;     for (int e = 0; e < 8; ++e) ss += v[e] * v[e];
;     ss += shx(ss, 1, lane); ss += shx(ss, 2, lane); ss += shx(ss, 4, lane);
;     const float rk = rsqrtf(ss * (1.0f / 64.0f) + 1e-6f);
;     u32x4 o; o.x = pk_bf16(v[0] * rk, v[1] * rk); o.y = pk_bf16(v[2] * rk, v[3] * rk); o.z = pk_bf16(v[4] * rk, v[5] * rk); o.w = pk_bf16(v[6] * rk, v[7] * rk); return o;
; }
; __device__ __forceinline__ void na_item(int wv, const Params& p, int l, int it, LAS unsigned char* lds) {
;     ...
;             for (int i = 0; i < 5; ++i) { const int e = tid + i * 512, key = e >> 3, seg = e & 7; *(LAS u32x4*)(lds + NB_KLOC + key * 144 + seg * 16) = norm_krow(kl[i], lane); }
.LBB0_746:
	s_or_b64 exec, exec, s[50:51]
	s_and_b64 vcc, exec, s[14:15]
	s_cbranch_vccnz .LBB0_748
	s_waitcnt vmcnt(4)
	v_lshlrev_b32_e32 v2, 16, v16
	v_and_b32_e32 v3, 0xffff0000, v16
	v_pk_mul_f32 v[84:85], v[2:3], v[2:3]
	v_and_b32_e32 v86, 0xffff0000, v17
	v_lshlrev_b32_e32 v87, 16, v17
	v_pk_mul_f32 v[88:89], v[86:87], v[86:87]
	v_add_f32_e32 v0, v84, v85
	v_and_b32_e32 v90, 0xffff0000, v18
	v_lshlrev_b32_e32 v91, 16, v18
	v_add_f32_e32 v0, v89, v0
	v_pk_mul_f32 v[92:93], v[90:91], v[90:91]
	v_add_f32_e32 v0, v88, v0
	v_and_b32_e32 v94, 0xffff0000, v19
	v_lshlrev_b32_e32 v95, 16, v19
	v_add_f32_e32 v0, v93, v0
	v_pk_mul_f32 v[96:97], v[94:95], v[94:95]
	v_add_f32_e32 v0, v92, v0
	v_add_f32_e32 v0, v97, v0
	v_add_f32_e32 v0, v96, v0
	s_nop 1
	v_add_f32_dpp v0, v0, v0 quad_perm:[1,0,3,2] row_mask:0xf bank_mask:0xf
	s_nop 1
	v_add_f32_dpp v0, v0, v0 quad_perm:[2,3,0,1] row_mask:0xf bank_mask:0xf
	s_nop 1
	v_add_f32_dpp v0, v0, v0 row_half_mirror row_mask:0xf bank_mask:0xf
	v_fmamk_f32 v0, v0, 0x3c800000, v197
	v_cmp_gt_f32_e32 vcc, s68, v0
	v_mul_f32_e32 v84, 0x4b800000, v0
	s_nop 0
	v_cndmask_b32_e32 v0, v0, v84, vcc
	v_rsq_f32_e32 v0, v0
	s_nop 0
	v_mul_f32_e32 v84, 0x45800000, v0
	v_cndmask_b32_e32 v0, v0, v84, vcc
	v_mul_f32_e32 v2, v0, v2
	v_mul_f32_e32 v3, v0, v3
	v_cvt_pk_bf16_f32 v84, v2, v3
	v_mul_f32_e32 v2, v0, v87
	v_mul_f32_e32 v3, v0, v86
	v_cvt_pk_bf16_f32 v85, v2, v3
	v_mul_f32_e32 v2, v0, v91
	v_mul_f32_e32 v3, v0, v90
	v_cvt_pk_bf16_f32 v86, v2, v3
	v_mul_f32_e32 v2, v0, v95
	v_mul_f32_e32 v0, v0, v94
	v_cvt_pk_bf16_f32 v87, v2, v0
	v_add_u32_e32 v0, v143, v160
	v_lshlrev_b32_e32 v2, 16, v12
	v_and_b32_e32 v3, 0xffff0000, v12
	ds_write_b128 v0, v[84:87]
	v_pk_mul_f32 v[84:85], v[2:3], v[2:3]
	v_and_b32_e32 v86, 0xffff0000, v13
	v_lshlrev_b32_e32 v87, 16, v13
	v_pk_mul_f32 v[88:89], v[86:87], v[86:87]
	v_add_f32_e32 v0, v84, v85
	v_and_b32_e32 v90, 0xffff0000, v14
	v_lshlrev_b32_e32 v91, 16, v14
	v_add_f32_e32 v0, v89, v0
	v_pk_mul_f32 v[92:93], v[90:91], v[90:91]
	v_add_f32_e32 v0, v88, v0
	v_and_b32_e32 v94, 0xffff0000, v15
	v_lshlrev_b32_e32 v95, 16, v15
	v_add_f32_e32 v0, v93, v0
	v_pk_mul_f32 v[96:97], v[94:95], v[94:95]
	v_add_f32_e32 v0, v92, v0
	v_add_f32_e32 v0, v97, v0
	v_add_f32_e32 v0, v96, v0
	s_nop 1
	v_add_f32_dpp v0, v0, v0 quad_perm:[1,0,3,2] row_mask:0xf bank_mask:0xf
	s_nop 1
	v_add_f32_dpp v0, v0, v0 quad_perm:[2,3,0,1] row_mask:0xf bank_mask:0xf
	s_nop 1
	v_add_f32_dpp v0, v0, v0 row_half_mirror row_mask:0xf bank_mask:0xf
	v_fmamk_f32 v0, v0, 0x3c800000, v197
	v_cmp_gt_f32_e32 vcc, s68, v0
	v_mul_f32_e32 v84, 0x4b800000, v0
	s_nop 0
	v_cndmask_b32_e32 v0, v0, v84, vcc
	v_rsq_f32_e32 v0, v0
	s_nop 0
	v_mul_f32_e32 v84, 0x45800000, v0
	v_cndmask_b32_e32 v0, v0, v84, vcc
	v_mul_f32_e32 v2, v0, v2
	v_mul_f32_e32 v3, v0, v3
	v_cvt_pk_bf16_f32 v84, v2, v3
	v_mul_f32_e32 v2, v0, v87
	v_mul_f32_e32 v3, v0, v86
	v_cvt_pk_bf16_f32 v85, v2, v3
	v_mul_f32_e32 v2, v0, v91
	v_mul_f32_e32 v3, v0, v90
	v_cvt_pk_bf16_f32 v86, v2, v3
	v_mul_f32_e32 v2, v0, v95
	v_mul_f32_e32 v0, v0, v94
	v_cvt_pk_bf16_f32 v87, v2, v0
	v_add_u32_e32 v0, v143, v161
	v_lshlrev_b32_e32 v2, 16, v20
	v_and_b32_e32 v3, 0xffff0000, v20
	ds_write_b128 v0, v[84:87]
	v_pk_mul_f32 v[84:85], v[2:3], v[2:3]
	v_and_b32_e32 v86, 0xffff0000, v21
	v_lshlrev_b32_e32 v87, 16, v21
	v_pk_mul_f32 v[88:89], v[86:87], v[86:87]
	v_add_f32_e32 v0, v84, v85
	v_and_b32_e32 v90, 0xffff0000, v22
	v_lshlrev_b32_e32 v91, 16, v22
	v_add_f32_e32 v0, v89, v0
	v_pk_mul_f32 v[92:93], v[90:91], v[90:91]
	v_add_f32_e32 v0, v88, v0
	v_and_b32_e32 v94, 0xffff0000, v23
	v_lshlrev_b32_e32 v95, 16, v23
	v_add_f32_e32 v0, v93, v0
	v_pk_mul_f32 v[96:97], v[94:95], v[94:95]
	v_add_f32_e32 v0, v92, v0
	v_add_f32_e32 v0, v97, v0
	v_add_f32_e32 v0, v96, v0
	s_nop 1
	v_add_f32_dpp v0, v0, v0 quad_perm:[1,0,3,2] row_mask:0xf bank_mask:0xf
	s_nop 1
	v_add_f32_dpp v0, v0, v0 quad_perm:[2,3,0,1] row_mask:0xf bank_mask:0xf
	s_nop 1
; #define LAS __attribute__((address_space(3)))
; __device__ __forceinline__ unsigned pk_bf16(float lo, float hi) { unsigned r; asm volatile("v_cvt_pk_bf16_f32 %0, %1, %2" : "=v"(r) : "v"(lo), "v"(hi)); return r; }
; __device__ __forceinline__ float bflo(unsigned w) { return __uint_as_float(w << 16); }
; __device__ __forceinline__ float bfhi(unsigned w) { return __uint_as_float(w & 0xffff0000u); }
; __device__ __forceinline__ float shx(float v, int m, int lane) { return __int_as_float(__builtin_amdgcn_ds_bpermute((lane ^ m) << 2, __float_as_int(v))); }
; __device__ __forceinline__ u32x4 norm_krow(u32x4 w, int lane) {
;     float v[8]; v[0] = bflo(w.x); v[1] = bfhi(w.x); v[2] = bflo(w.y); v[3] = bfhi(w.y); v[4] = bflo(w.z); v[5] = bfhi(w.z); v[6] = bflo(w.w); v[7] = bfhi(w.w);
;     float ss = 0.f;
; #pragma unroll
;     for (int e = 0; e < 8; ++e) ss += v[e] * v[e];
;     ss += shx(ss, 1, lane); ss += shx(ss, 2, lane); ss += shx(ss, 4, lane);
;     const float rk = rsqrtf(ss * (1.0f / 64.0f) + 1e-6f);
;     u32x4 o; o.x = pk_bf16(v[0] * rk, v[1] * rk); o.y = pk_bf16(v[2] * rk, v[3] * rk); o.z = pk_bf16(v[4] * rk, v[5] * rk); o.w = pk_bf16(v[6] * rk, v[7] * rk); return o;
; }
; __device__ __forceinline__ void na_item(int wv, const Params& p, int l, int it, LAS unsigned char* lds) {
;     ...
;             for (int i = 0; i < 5; ++i) { const int e = tid + i * 512, key = e >> 3, seg = e & 7; *(LAS u32x4*)(lds + NB_KLOC + key * 144 + seg * 16) = norm_krow(kl[i], lane); }
; #pragma unroll
;             for (int i = 0; i < 5; ++i) { const int e = tid + i * 512, d = e / 40, seg = e % 40; *(LAS u32x4*)(lds + NB_VLOC + d * 656 + seg * 16) = vl[i]; }
	v_add_f32_dpp v0, v0, v0 row_half_mirror row_mask:0xf bank_mask:0xf
	v_fmamk_f32 v0, v0, 0x3c800000, v197
	v_cmp_gt_f32_e32 vcc, s68, v0
	v_mul_f32_e32 v84, 0x4b800000, v0
	s_nop 0
	v_cndmask_b32_e32 v0, v0, v84, vcc
	v_rsq_f32_e32 v0, v0
	s_nop 0
	v_mul_f32_e32 v84, 0x45800000, v0
	v_cndmask_b32_e32 v0, v0, v84, vcc
	v_mul_f32_e32 v2, v0, v2
	v_mul_f32_e32 v3, v0, v3
	v_cvt_pk_bf16_f32 v84, v2, v3
	v_mul_f32_e32 v2, v0, v87
	v_mul_f32_e32 v3, v0, v86
	v_cvt_pk_bf16_f32 v85, v2, v3
	v_mul_f32_e32 v2, v0, v91
	v_mul_f32_e32 v3, v0, v90
	v_cvt_pk_bf16_f32 v86, v2, v3
	v_mul_f32_e32 v2, v0, v95
	v_mul_f32_e32 v0, v0, v94
	v_cvt_pk_bf16_f32 v87, v2, v0
	v_lshlrev_b32_e32 v2, 16, v24
	v_and_b32_e32 v3, 0xffff0000, v24
	ds_write_b128 v176, v[84:87]
	v_pk_mul_f32 v[84:85], v[2:3], v[2:3]
	v_and_b32_e32 v86, 0xffff0000, v25
	v_lshlrev_b32_e32 v87, 16, v25
	v_pk_mul_f32 v[88:89], v[86:87], v[86:87]
	v_add_f32_e32 v0, v84, v85
	v_and_b32_e32 v90, 0xffff0000, v26
	v_lshlrev_b32_e32 v91, 16, v26
	v_add_f32_e32 v0, v89, v0
	v_pk_mul_f32 v[92:93], v[90:91], v[90:91]
	v_add_f32_e32 v0, v88, v0
	v_and_b32_e32 v94, 0xffff0000, v27
	v_lshlrev_b32_e32 v95, 16, v27
	v_add_f32_e32 v0, v93, v0
	v_pk_mul_f32 v[96:97], v[94:95], v[94:95]
	v_add_f32_e32 v0, v92, v0
	v_add_f32_e32 v0, v97, v0
	v_add_f32_e32 v0, v96, v0
	s_nop 1
	v_add_f32_dpp v0, v0, v0 quad_perm:[1,0,3,2] row_mask:0xf bank_mask:0xf
	s_nop 1
	v_add_f32_dpp v0, v0, v0 quad_perm:[2,3,0,1] row_mask:0xf bank_mask:0xf
	s_nop 1
	v_add_f32_dpp v0, v0, v0 row_half_mirror row_mask:0xf bank_mask:0xf
	v_fmamk_f32 v0, v0, 0x3c800000, v197
	v_cmp_gt_f32_e32 vcc, s68, v0
	v_mul_f32_e32 v84, 0x4b800000, v0
	s_nop 0
	v_cndmask_b32_e32 v0, v0, v84, vcc
	v_rsq_f32_e32 v0, v0
	s_nop 0
	v_mul_f32_e32 v84, 0x45800000, v0
	v_cndmask_b32_e32 v0, v0, v84, vcc
	v_mul_f32_e32 v2, v0, v2
	v_mul_f32_e32 v3, v0, v3
	v_cvt_pk_bf16_f32 v84, v2, v3
	v_mul_f32_e32 v2, v0, v87
	v_mul_f32_e32 v3, v0, v86
	v_cvt_pk_bf16_f32 v85, v2, v3
	v_mul_f32_e32 v2, v0, v91
	v_mul_f32_e32 v3, v0, v90
	v_cvt_pk_bf16_f32 v86, v2, v3
	v_mul_f32_e32 v2, v0, v95
	v_mul_f32_e32 v0, v0, v94
	v_cvt_pk_bf16_f32 v87, v2, v0
	v_lshlrev_b32_e32 v2, 16, v28
	v_and_b32_e32 v3, 0xffff0000, v28
	ds_write_b128 v177, v[84:87]
	v_pk_mul_f32 v[84:85], v[2:3], v[2:3]
	v_and_b32_e32 v86, 0xffff0000, v29
	v_lshlrev_b32_e32 v87, 16, v29
	v_pk_mul_f32 v[88:89], v[86:87], v[86:87]
	v_add_f32_e32 v0, v84, v85
	v_and_b32_e32 v90, 0xffff0000, v30
	v_lshlrev_b32_e32 v91, 16, v30
	v_add_f32_e32 v0, v89, v0
	v_pk_mul_f32 v[92:93], v[90:91], v[90:91]
	v_add_f32_e32 v0, v88, v0
	v_and_b32_e32 v94, 0xffff0000, v31
	v_lshlrev_b32_e32 v95, 16, v31
	v_add_f32_e32 v0, v93, v0
	v_pk_mul_f32 v[96:97], v[94:95], v[94:95]
	v_add_f32_e32 v0, v92, v0
	v_add_f32_e32 v0, v97, v0
	v_add_f32_e32 v0, v96, v0
	s_nop 1
	v_add_f32_dpp v0, v0, v0 quad_perm:[1,0,3,2] row_mask:0xf bank_mask:0xf
	s_nop 1
	v_add_f32_dpp v0, v0, v0 quad_perm:[2,3,0,1] row_mask:0xf bank_mask:0xf
	s_nop 1
	v_add_f32_dpp v0, v0, v0 row_half_mirror row_mask:0xf bank_mask:0xf
	v_fmamk_f32 v0, v0, 0x3c800000, v197
	v_cmp_gt_f32_e32 vcc, s68, v0
	v_mul_f32_e32 v84, 0x4b800000, v0
	s_nop 0
	v_cndmask_b32_e32 v0, v0, v84, vcc
	v_rsq_f32_e32 v0, v0
	s_nop 0
	v_mul_f32_e32 v84, 0x45800000, v0
	v_cndmask_b32_e32 v0, v0, v84, vcc
	v_mul_f32_e32 v2, v0, v2
	v_mul_f32_e32 v3, v0, v3
	v_cvt_pk_bf16_f32 v84, v2, v3
	v_mul_f32_e32 v2, v0, v87
	v_mul_f32_e32 v3, v0, v86
	v_cvt_pk_bf16_f32 v85, v2, v3
	v_mul_f32_e32 v2, v0, v91
	v_mul_f32_e32 v3, v0, v90
	v_cvt_pk_bf16_f32 v86, v2, v3
	v_mul_f32_e32 v2, v0, v95
	v_mul_f32_e32 v0, v0, v94
	v_cvt_pk_bf16_f32 v87, v2, v0
	ds_write_b128 v178, v[84:87]
	s_waitcnt vmcnt(8)
	ds_write_b128 v179, v[32:35] offset:46080
	s_waitcnt vmcnt(7)
	ds_write_b128 v180, v[36:39] offset:46080
	s_waitcnt vmcnt(6)
	ds_write_b128 v181, v[40:43] offset:46080
	s_waitcnt vmcnt(5)
	ds_write_b128 v182, v[44:47] offset:46080
	s_waitcnt vmcnt(4)
	ds_write_b128 v183, v[48:51] offset:46080
